# prep waves: y-partial reduction as 15 plain adds (same sum tree) instead of shuffles + packed adds
# speedup vs baseline: 1.0197x; 1.0034x over previous
.LBB0_641:
	s_add_i32 s35, s50, 2
	s_and_saveexec_b64 s[46:47], s[0:1]
	s_xor_b64 s[46:47], exec, s[46:47]
	s_cbranch_execz .LBB0_650
	s_cmp_eq_u32 s50, -2
	s_mov_b32 s51, 0
	s_cbranch_scc1 .LBB0_644
	v_add_u32_e32 v34, v33, v53
	ds_read_b128 v[24:27], v34 offset:59392
	ds_read_b128 v[28:31], v34 offset:59424
	ds_read_b128 v[98:101], v34 offset:59408
	ds_read_b128 v[102:105], v34 offset:59440
	s_add_i32 s18, s15, -16
	s_mov_b32 s51, s15
	s_waitcnt lgkmcnt(0)
	v_add_f32_e32 v24, v24, v25
	v_add_f32_e32 v26, v26, v27
	v_add_f32_e32 v24, v24, v26
	v_add_f32_e32 v98, v98, v99
	v_add_f32_e32 v100, v100, v101
	v_add_f32_e32 v98, v98, v100
	v_add_f32_e32 v24, v24, v98
	v_add_f32_e32 v28, v28, v29
	v_add_f32_e32 v30, v30, v31
	v_add_f32_e32 v28, v28, v30
	v_add_f32_e32 v102, v102, v103
	v_add_f32_e32 v104, v104, v105
	v_add_f32_e32 v102, v102, v104
	v_add_f32_e32 v28, v28, v102
	v_add_f32_e32 v26, v24, v28
	v_lshl_add_u64 v[24:25], v[72:73], 0, s[18:19]
	v_lshlrev_b64 v[24:25], 11, v[24:25]
	v_lshl_add_u64 v[24:25], v[76:77], 0, v[24:25]
	global_store_dword v[24:25], v26, off

.LBB0_652:
	s_or_b64 exec, exec, s[46:47]
	s_waitcnt lgkmcnt(0)
	s_barrier
	s_and_saveexec_b64 s[46:47], s[0:1]
	s_xor_b64 s[46:47], exec, s[46:47]
	s_cbranch_execz .LBB0_660
	v_add_u32_e32 v34, v33, v53
	ds_read_b128 v[24:27], v34 offset:43008
	ds_read_b128 v[28:31], v34 offset:43040
	ds_read_b128 v[98:101], v34 offset:43024
	ds_read_b128 v[102:105], v34 offset:43056
	s_add_i32 s18, s50, 3
	s_cmpk_gt_u32 s18, 0xfe
	s_waitcnt lgkmcnt(0)
	v_add_f32_e32 v24, v24, v25
	v_add_f32_e32 v26, v26, v27
	v_add_f32_e32 v24, v24, v26
	v_add_f32_e32 v98, v98, v99
	v_add_f32_e32 v100, v100, v101
	v_add_f32_e32 v98, v98, v100
	v_add_f32_e32 v24, v24, v98
	v_add_f32_e32 v28, v28, v29
	v_add_f32_e32 v30, v30, v31
	v_add_f32_e32 v28, v28, v30
	v_add_f32_e32 v102, v102, v103
	v_add_f32_e32 v104, v104, v105
	v_add_f32_e32 v102, v102, v104
	v_add_f32_e32 v28, v28, v102
	v_add_f32_e32 v26, v24, v28
	v_lshl_add_u64 v[24:25], s[72:73], 0, v[84:85]
	global_store_dword v[24:25], v26, off
	s_cbranch_scc1 .LBB0_660
	s_waitcnt vmcnt(9)
	v_lshlrev_b32_e32 v24, 16, v54
	s_waitcnt vmcnt(8)
	v_lshlrev_b32_e32 v34, 16, v56
	s_waitcnt vmcnt(3)
	v_lshlrev_b32_e32 v114, 16, v66
	v_sub_f32_e32 v106, v34, v24
	v_mul_f32_e32 v34, 0xbf1b4598, v114
	v_and_b32_e32 v25, 0xffff0000, v54
	v_and_b32_e32 v98, 0xffff0000, v56
	v_and_b32_e32 v115, 0xffff0000, v66
	v_mul_f32_e32 v34, 0x3fb8aa3b, v34
	v_sub_f32_e32 v107, v98, v25
	v_exp_f32_e32 v98, v34
	v_mul_f32_e32 v34, 0xbf1b4598, v115
	v_lshlrev_b32_e32 v26, 16, v55
	v_lshlrev_b32_e32 v99, 16, v57
	v_lshlrev_b32_e32 v116, 16, v67
	v_mul_f32_e32 v34, 0x3fb8aa3b, v34
	v_sub_f32_e32 v108, v99, v26
	v_exp_f32_e32 v99, v34
	v_mul_f32_e32 v34, 0xbf1b4598, v116
	v_and_b32_e32 v27, 0xffff0000, v55
	v_and_b32_e32 v100, 0xffff0000, v57
	v_and_b32_e32 v117, 0xffff0000, v67
	v_mul_f32_e32 v34, 0x3fb8aa3b, v34
	v_sub_f32_e32 v109, v100, v27
	v_exp_f32_e32 v100, v34
	v_mul_f32_e32 v34, 0xbf1b4598, v117
	v_lshlrev_b32_e32 v28, 16, v58
	v_and_b32_e32 v29, 0xffff0000, v58
	v_lshlrev_b32_e32 v101, 16, v60
	v_and_b32_e32 v112, 0xffff0000, v60
	v_mul_f32_e32 v34, 0x3fb8aa3b, v34
	v_sub_f32_e32 v113, v112, v29
	v_sub_f32_e32 v112, v101, v28
	v_exp_f32_e32 v101, v34
	v_lshlrev_b32_e32 v30, 16, v59
	v_and_b32_e32 v31, 0xffff0000, v59
	v_lshlrev_b32_e32 v110, 16, v61
	v_and_b32_e32 v111, 0xffff0000, v61
	v_sub_f32_e32 v111, v111, v31
	v_sub_f32_e32 v110, v110, v30
	s_waitcnt vmcnt(2)
	v_pk_fma_f32 v[26:27], v[18:19], v[108:109], v[26:27]
	v_pk_fma_f32 v[108:109], v[14:15], v[110:111], v[30:31]
	v_lshlrev_b32_e32 v102, 16, v68
	v_and_b32_e32 v103, 0xffff0000, v68
	v_lshlrev_b32_e32 v104, 16, v69
	v_and_b32_e32 v105, 0xffff0000, v69
	v_pk_fma_f32 v[24:25], v[16:17], v[106:107], v[24:25]
	v_pk_fma_f32 v[106:107], v[12:13], v[112:113], v[28:29]
	ds_write_b128 v93, v[98:101]
	v_pk_mul_f32 v[98:99], v[10:11], v[108:109] neg_lo:[0,1] neg_hi:[0,1]
	v_pk_add_f32 v[28:29], v[104:105], -1.0 op_sel_hi:[1,0]
	v_pk_add_f32 v[30:31], v[102:103], -1.0 op_sel_hi:[1,0]
	s_waitcnt vmcnt(1)
	v_pk_mul_f32 v[100:101], v[70:71], v[98:99] op_sel_hi:[0,1]
	v_pk_mul_f32 v[98:99], v[8:9], v[106:107] neg_lo:[0,1] neg_hi:[0,1]
	v_pk_fma_f32 v[110:111], v[0:1], v[30:31], 1.0 op_sel_hi:[1,1,0]
	v_pk_fma_f32 v[28:29], v[2:3], v[28:29], 1.0 op_sel_hi:[1,1,0]
	v_pk_mul_f32 v[98:99], v[70:71], v[98:99] op_sel_hi:[0,1]
	v_pk_mul_f32 v[30:31], v[28:29], v[108:109]
	v_pk_mul_f32 v[28:29], v[110:111], v[106:107]
	ds_write_b128 v93, v[98:101] offset:256
	v_pk_mul_f32 v[100:101], v[100:101], v[104:105] neg_lo:[1,0] neg_hi:[1,0]
	v_pk_mul_f32 v[98:99], v[98:99], v[102:103] neg_lo:[1,0] neg_hi:[1,0]
	ds_write_b128 v93, v[98:101] offset:512
	ds_write_b128 v93, v[28:31] offset:768
	ds_write_b128 v93, v[24:27] offset:1024
	s_and_saveexec_b64 s[48:49], s[2:3]
	s_cbranch_execz .LBB0_656
	v_lshlrev_b32_e32 v34, 16, v64
	v_and_b32_e32 v102, 0xffff0000, v64
	v_lshlrev_b32_e32 v104, 16, v65
	v_and_b32_e32 v105, 0xffff0000, v65
	v_lshlrev_b32_e32 v98, 16, v62
	v_and_b32_e32 v99, 0xffff0000, v62
	v_lshlrev_b32_e32 v100, 16, v63
	v_and_b32_e32 v101, 0xffff0000, v63
	v_sub_f32_e32 v103, v102, v99
	v_sub_f32_e32 v102, v34, v98
	v_sub_f32_e32 v105, v105, v101
	v_sub_f32_e32 v104, v104, v100
	v_pk_fma_f32 v[100:101], v[22:23], v[104:105], v[100:101]
	v_pk_fma_f32 v[98:99], v[20:21], v[102:103], v[98:99]
	ds_write_b128 v94, v[98:101] offset:40960
